# attention: next tile's K fragments read from LDS right after the step barrier (overlapping the softmax), QK MFMAs start without LDS wait
# speedup vs baseline: 1.0342x; 1.0342x over previous
.LBB0_736:
	v_mov_b32_e32 v14, v137
	v_mov_b32_e32 v15, v137
	s_addk_i32 s28, 0x100
	v_mul_u32_u24_e32 v147, 0xd0, v10
	v_mul_u32_u24_e32 v156, 0x90, v10
	v_lshlrev_b32_e32 v145, 2, v11
	v_mad_u64_u32 v[148:149], s[2:3], v140, 3, v[4:5]
	v_mad_u64_u32 v[150:151], s[2:3], v138, 3, v[2:3]
	v_mad_u64_u32 v[152:153], s[2:3], v136, 3, v[0:1]
	v_mov_b32_e32 v0, v137
	v_mov_b32_e32 v1, v137
	v_mov_b32_e32 v2, v137
	v_mov_b32_e32 v3, v137
	v_mov_b32_e32 v4, v137
	v_mov_b32_e32 v5, v137
	v_mov_b32_e32 v6, v137
	v_mov_b32_e32 v7, v137
	v_mov_b32_e32 v8, v137
	v_mov_b32_e32 v9, v137
	v_mov_b32_e32 v10, v137
	v_mov_b32_e32 v11, v137
	v_mov_b32_e32 v12, v137
	v_mov_b32_e32 v13, v137
	v_mov_b64_e32 v[30:31], v[14:15]
	s_lshr_b32 s46, s28, 6
	s_or_b32 s47, s44, 31
	s_mov_b32 s48, 0
	v_mov_b32_e32 v157, 0
	s_mov_b32 s49, 63
	v_mov_b64_e32 v[28:29], v[12:13]
	v_mov_b64_e32 v[26:27], v[10:11]
	v_mov_b64_e32 v[24:25], v[8:9]
	v_mov_b64_e32 v[22:23], v[6:7]
	v_mov_b64_e32 v[20:21], v[4:5]
	v_mov_b64_e32 v[18:19], v[2:3]
	v_mov_b64_e32 v[16:17], v[0:1]
	v_mov_b32_e32 v158, 0
	v_mov_b32_e32 v64, 0
	v_mov_b32_e32 v216, 0
	v_mov_b32_e32 v217, 0
	v_mov_b32_e32 v218, 0
	v_mov_b32_e32 v219, 0
	v_mov_b32_e32 v220, 0
	v_mov_b32_e32 v221, 0
	v_mov_b32_e32 v222, 0
	v_mov_b32_e32 v223, 0
	v_mov_b32_e32 v224, 0
	v_mov_b32_e32 v225, 0
	v_mov_b32_e32 v226, 0
	v_mov_b32_e32 v227, 0
	v_mov_b32_e32 v228, 0
	v_mov_b32_e32 v229, 0
	v_mov_b32_e32 v230, 0
	v_mov_b32_e32 v231, 0
	s_waitcnt vmcnt(0)
	v_add_u32_e32 v159, v147, v146
	ds_read_b128 v[168:171], v159
	ds_read_b128 v[192:195], v159 offset:6656
	ds_read_b128 v[172:175], v159 offset:32
	ds_read_b128 v[196:199], v159 offset:6688
	ds_read_b128 v[176:179], v159 offset:64
	ds_read_b128 v[200:203], v159 offset:6720
	ds_read_b128 v[180:183], v159 offset:96
	ds_read_b128 v[204:207], v159 offset:6752
	ds_read_b128 v[184:187], v159 offset:128
	ds_read_b128 v[208:211], v159 offset:6784
	ds_read_b128 v[188:191], v159 offset:160
	ds_read_b128 v[212:215], v159 offset:6816
	s_branch .LBB0_740

.LBB0_739:
	s_add_i32 s48, s48, 1
	s_add_i32 s49, s49, 64
	v_lshl_add_u64 v[148:149], v[148:149], 0, v[140:141]
	v_lshl_add_u64 v[150:151], v[150:151], 0, v[138:139]
	s_cmp_ge_u32 s48, s46
	v_lshl_add_u64 v[152:153], v[152:153], 0, v[136:137]
	s_cbranch_scc1 .LBB0_759

.LBB0_743:
	s_sub_i32 s26, s49, 63
	s_cmp_le_i32 s26, s47
	s_cselect_b64 s[28:29], -1, 0
	s_cmp_gt_i32 s26, s47
	s_cbranch_scc1 .LBB0_756
	s_and_b32 s26, s48, 3
	s_mulk_i32 s26, 0x5800
	s_add_i32 s26, s26, 0
	v_add3_u32 v232, s26, v156, v146
	s_waitcnt lgkmcnt(0)
	v_mfma_f32_32x32x16_bf16 v[32:47], v[168:171], v[96:99], v[216:231]
	v_mfma_f32_32x32x16_bf16 v[48:63], v[192:195], v[96:99], v[216:231]
	ds_read_b128 v[108:111], v232 offset:13312
	ds_read_b128 v[124:127], v232 offset:17920
	v_mfma_f32_32x32x16_bf16 v[32:47], v[172:175], v[80:83], v[32:47]
	v_mfma_f32_32x32x16_bf16 v[48:63], v[196:199], v[80:83], v[48:63]
	ds_read_b128 v[104:107], v232 offset:13344
	ds_read_b128 v[120:123], v232 offset:17952
	v_mfma_f32_32x32x16_bf16 v[32:47], v[176:179], v[84:87], v[32:47]
	v_mfma_f32_32x32x16_bf16 v[48:63], v[200:203], v[84:87], v[48:63]
	ds_read_b128 v[112:115], v232 offset:13376
	ds_read_b128 v[132:135], v232 offset:17984
	v_mfma_f32_32x32x16_bf16 v[32:47], v[180:183], v[88:91], v[32:47]
	v_mfma_f32_32x32x16_bf16 v[48:63], v[204:207], v[88:91], v[48:63]
	ds_read_b128 v[116:119], v232 offset:13408
	ds_read_b128 v[128:131], v232 offset:18016
	v_mfma_f32_32x32x16_bf16 v[32:47], v[184:187], v[92:95], v[32:47]
	v_mfma_f32_32x32x16_bf16 v[48:63], v[208:211], v[92:95], v[48:63]
	v_mfma_f32_32x32x16_bf16 v[32:47], v[188:191], v[100:103], v[32:47]
	v_mfma_f32_32x32x16_bf16 v[48:63], v[212:215], v[100:103], v[48:63]
	s_mov_b64 s[26:27], -1
	s_and_b64 vcc, exec, s[2:3]
	s_cbranch_vccnz .LBB0_757

.LBB0_747:
	s_waitcnt lgkmcnt(0)
	s_barrier
	s_andn2_b64 vcc, exec, s[28:29]
	s_cbranch_vccnz .LBB0_739
	s_add_i32 s26, s48, 1
	s_cmp_ge_u32 s26, s46
	s_cbranch_scc1 .Lkpf_done
	s_add_i32 s27, s49, 1
	s_cmp_gt_i32 s27, s47
	s_cbranch_scc1 .Lkpf_done
	s_and_b32 s26, s26, 3
	s_mulk_i32 s26, 0x5800
	v_add3_u32 v159, s26, v147, v146
	ds_read_b128 v[168:171], v159
	ds_read_b128 v[192:195], v159 offset:6656
	ds_read_b128 v[172:175], v159 offset:32
	ds_read_b128 v[196:199], v159 offset:6688
	ds_read_b128 v[176:179], v159 offset:64
	ds_read_b128 v[200:203], v159 offset:6720
	ds_read_b128 v[180:183], v159 offset:96
	ds_read_b128 v[204:207], v159 offset:6752
	ds_read_b128 v[184:187], v159 offset:128
	ds_read_b128 v[208:211], v159 offset:6784
	ds_read_b128 v[188:191], v159 offset:160
	ds_read_b128 v[212:215], v159 offset:6816
.Lkpf_done:
	s_cmp_le_i32 s49, s44
	s_cbranch_scc1 .LBB0_750
	v_add_u32_e32 v65, s49, v145
	v_subrev_u32_e32 v67, 31, v65
	v_subrev_u32_e32 v66, 63, v65
	v_cmp_le_i32_e32 vcc, v67, v144
	s_nop 1
	v_cndmask_b32_e32 v48, v155, v48, vcc
	v_cmp_lt_i32_e32 vcc, v66, v144
	s_nop 1
	v_cndmask_b32_e32 v33, v155, v33, vcc
	v_cmp_le_i32_e32 vcc, v66, v144
	v_subrev_u32_e32 v66, 30, v65
	s_nop 0
	v_cndmask_b32_e32 v32, v155, v32, vcc
	v_cmp_le_i32_e32 vcc, v66, v144
	v_subrev_u32_e32 v66, 61, v65
	s_nop 0
	v_cndmask_b32_e32 v49, v155, v49, vcc
	v_cmp_le_i32_e32 vcc, v66, v144
	v_subrev_u32_e32 v66, 29, v65
	s_nop 0
	v_cndmask_b32_e32 v34, v155, v34, vcc
	v_cmp_le_i32_e32 vcc, v66, v144
	v_subrev_u32_e32 v66, 60, v65
	s_nop 0
	v_cndmask_b32_e32 v50, v155, v50, vcc
	v_cmp_le_i32_e32 vcc, v66, v144
	v_subrev_u32_e32 v66, 28, v65
	s_nop 0
	v_cndmask_b32_e32 v35, v155, v35, vcc
	v_cmp_le_i32_e32 vcc, v66, v144
	v_subrev_u32_e32 v66, 55, v65
	s_nop 0
	v_cndmask_b32_e32 v51, v155, v51, vcc
	v_cmp_le_i32_e32 vcc, v66, v144
	v_subrev_u32_e32 v66, 23, v65
	s_nop 0
	v_cndmask_b32_e32 v36, v155, v36, vcc
	v_cmp_le_i32_e32 vcc, v66, v144
	v_subrev_u32_e32 v66, 54, v65
	s_nop 0
	v_cndmask_b32_e32 v52, v155, v52, vcc
	v_cmp_le_i32_e32 vcc, v66, v144
	v_subrev_u32_e32 v66, 22, v65
	s_nop 0
	v_cndmask_b32_e32 v37, v155, v37, vcc
	v_cmp_le_i32_e32 vcc, v66, v144
	v_subrev_u32_e32 v66, 53, v65
	s_nop 0
	v_cndmask_b32_e32 v53, v155, v53, vcc
	v_cmp_le_i32_e32 vcc, v66, v144
	v_subrev_u32_e32 v66, 21, v65
	s_nop 0
	v_cndmask_b32_e32 v38, v155, v38, vcc
	v_cmp_le_i32_e32 vcc, v66, v144
	v_subrev_u32_e32 v66, 52, v65
	s_nop 0
	v_cndmask_b32_e32 v54, v155, v54, vcc
	v_cmp_le_i32_e32 vcc, v66, v144
	v_subrev_u32_e32 v66, 20, v65
	s_nop 0
	v_cndmask_b32_e32 v39, v155, v39, vcc
	v_cmp_le_i32_e32 vcc, v66, v144
	v_subrev_u32_e32 v66, 47, v65
	s_nop 0
	v_cndmask_b32_e32 v55, v155, v55, vcc
	v_cmp_le_i32_e32 vcc, v66, v144
	v_add_u32_e32 v66, -15, v65
	s_nop 0
	v_cndmask_b32_e32 v40, v155, v40, vcc
	v_cmp_le_i32_e32 vcc, v66, v144
	v_subrev_u32_e32 v66, 46, v65
	s_nop 0
	v_cndmask_b32_e32 v56, v155, v56, vcc
	v_cmp_le_i32_e32 vcc, v66, v144
	v_add_u32_e32 v66, -14, v65
	s_nop 0
	v_cndmask_b32_e32 v41, v155, v41, vcc
	v_cmp_le_i32_e32 vcc, v66, v144
	v_subrev_u32_e32 v66, 45, v65
	s_nop 0
	v_cndmask_b32_e32 v57, v155, v57, vcc
	v_cmp_le_i32_e32 vcc, v66, v144
	v_add_u32_e32 v66, -13, v65
	s_nop 0
	v_cndmask_b32_e32 v42, v155, v42, vcc
	v_cmp_le_i32_e32 vcc, v66, v144
	v_subrev_u32_e32 v66, 44, v65
	s_nop 0
	v_cndmask_b32_e32 v58, v155, v58, vcc
	v_cmp_le_i32_e32 vcc, v66, v144
	v_add_u32_e32 v66, -12, v65
	s_nop 0
	v_cndmask_b32_e32 v43, v155, v43, vcc
	v_cmp_le_i32_e32 vcc, v66, v144
	v_subrev_u32_e32 v66, 39, v65
	s_nop 0
	v_cndmask_b32_e32 v59, v155, v59, vcc
	v_cmp_le_i32_e32 vcc, v66, v144
	v_add_u32_e32 v66, -7, v65
	s_nop 0
	v_cndmask_b32_e32 v44, v155, v44, vcc
	v_cmp_le_i32_e32 vcc, v66, v144
	v_subrev_u32_e32 v66, 38, v65
	s_nop 0
	v_cndmask_b32_e32 v60, v155, v60, vcc
	v_cmp_le_i32_e32 vcc, v66, v144
	v_add_u32_e32 v66, -6, v65
	s_nop 0
	v_cndmask_b32_e32 v45, v155, v45, vcc
	v_cmp_le_i32_e32 vcc, v66, v144
	v_subrev_u32_e32 v66, 37, v65
	s_nop 0
	v_cndmask_b32_e32 v61, v155, v61, vcc
	v_cmp_le_i32_e32 vcc, v66, v144
	v_add_u32_e32 v66, -5, v65
	s_nop 0
	v_cndmask_b32_e32 v46, v155, v46, vcc
	v_cmp_le_i32_e32 vcc, v66, v144
	v_subrev_u32_e32 v66, 36, v65
	v_add_u32_e32 v65, -4, v65
	v_cndmask_b32_e32 v62, v155, v62, vcc
	v_cmp_le_i32_e32 vcc, v66, v144
	s_nop 1
	v_cndmask_b32_e32 v47, v155, v47, vcc
	v_cmp_le_i32_e32 vcc, v65, v144
	s_nop 1
	v_cndmask_b32_e32 v63, v155, v63, vcc
